# P9: all 8 waves run the same routing code path (the else-copy of the routing loop is no longer entered): half the instruction footprint in the shared I-cache
# speedup vs baseline: 1.0016x; 1.0016x over previous
.LBB0_783:
	s_cmp_lt_i32 s74, 10
	s_cselect_b64 s[0:1], -1, 0
	s_cmp_gt_i32 s75, 9
	s_cselect_b64 s[2:3], -1, 0
	s_and_b64 s[0:1], s[0:1], s[2:3]
	s_andn2_b64 vcc, exec, s[0:1]
	s_cbranch_vccnz .LBB0_864
	s_ashr_i32 s19, s18, 31
	s_ashr_i32 s91, s90, 31
	s_lshl_b64 s[0:1], s[18:19], 9
	s_lshl_b64 s[4:5], s[90:91], 9
	s_add_u32 s2, s72, 0xab00000
	s_addc_u32 s3, s73, 0
	s_add_u32 s6, s72, 0x2200000
	s_addc_u32 s7, s73, 0
	s_add_u32 s8, s72, 0x1eb00000
	s_addc_u32 s9, s73, 0
	s_add_u32 s10, s72, 0x1f300000
	v_readlane_b32 s91, v243, 0
	s_addc_u32 s11, s73, 0
	s_lshl_b32 s12, s90, 3
	s_add_i32 s19, s12, s91
	s_and_b32 s99, s19, 0x7ff
	s_load_dwordx2 s[92:93], s[68:69], 0x58
	s_load_dwordx2 s[94:95], s[68:69], 0x60
	s_lshl_b32 s52, s99, 13
	s_lshl_b32 s53, s99, 10
	s_add_u32 s46, s72, 0x2b00000
	s_addc_u32 s47, s73, 0
	s_add_u32 s46, s46, s53
	s_addc_u32 s47, s47, 0
	s_add_u32 s48, s46, 0x1800000
	s_addc_u32 s49, s47, 0
	s_waitcnt lgkmcnt(0)
	s_add_u32 s92, s92, s52
	s_addc_u32 s93, s93, 0
	s_add_u32 s94, s94, s52
	s_addc_u32 s95, s95, 0
	s_mov_b32 s98, 0
	v_mov_b32_e32 v244, 0x1000000
	v_mov_b32_e32 v245, 0
	v_mov_b32_e32 v246, 0x200000
	v_mov_b32_e32 v247, 0
	v_mov_b32_e32 v250, 0x1000
	v_mov_b32_e32 v251, 0
	s_lshl_b32 s12, s91, 13
	v_and_b32_e32 v76, 0x3f0, v1
	v_mov_b32_e32 v77, 0
	s_lshl_b32 s21, s18, 3
	s_add_i32 s26, s12, 0
	v_lshl_add_u64 v[2:3], s[72:73], 0, v[76:77]
	s_mov_b64 s[14:15], 0x2b00000
	s_cmpk_lt_i32 s19, 0x1000
	v_or_b32_e32 v70, s4, v0
	v_mov_b32_e32 v71, s5
	s_mov_b64 s[4:5], 0x100000
	v_lshl_add_u64 v[74:75], v[2:3], 0, s[14:15]
	s_mov_b64 s[14:15], 0x4300000
	s_cselect_b64 s[12:13], -1, 0
	s_cmpk_gt_u32 s76, 0xff
	v_cmp_gt_u64_e64 s[4:5], s[4:5], v[70:71]
	v_lshl_add_u64 v[72:73], v[2:3], 0, s[14:15]
	v_and_b32_e32 v1, 63, v0
	s_mov_b64 s[14:15], -1
	s_and_b64 vcc, exec, s[14:15]
	s_cbranch_vccnz .LBB0_799
